# gMLP: exact prefetch waits (latch vmcnt(4) -> 16/10 by refill flag, B-unit U values staged in v[140:147] and moved at B-top, A-top waits removed)
# speedup vs baseline: 1.0068x; 1.0068x over previous
; __device__ __forceinline__ int lane_id() { int l; asm volatile("v_mbcnt_lo_u32_b32 %0, -1, 0\n\tv_mbcnt_hi_u32_b32 %0, -1, %0" : "=v"(l)); return l; }
; #define LAS __attribute__((address_space(3)))
; __global__ void __launch_bounds__(NWAVES * 64, 2) mk_fwd(Args args) {
;     extern __shared__ __attribute__((aligned(16))) unsigned char lds[];
;     LAS unsigned char* L = (LAS unsigned char*)lds;
;     volatile LAS unsigned* MISC = (volatile LAS unsigned*)(L + MISC_OFF);
;     const int wid0 = __builtin_amdgcn_readfirstlane((int)threadIdx.x >> 6);
;     const int G = gridDim.x, bx = blockIdx.x;
;     { const int t0 = wid0 * 64 + lane_id(); for (int u = t0; u < (LDS_BYTES - LDSCTL_OFF) / 4; u += NWAVES * 64) ((LAS unsigned*)(L + LDSCTL_OFF))[u] = 0u; }
_Z6mk_fwd4Args:
	v_readfirstlane_b32 s3, v0
	s_mov_b64 s[86:87], s[0:1]
	s_mov_b32 s98, 0
	s_and_b32 s0, s3, 0xffffffc0
	s_add_u32 s4, s86, 0xc0
	s_addc_u32 s5, s87, 0
	s_load_dword s85, s[86:87], 0xc0
	v_writelane_b32 v238, s4, 0
	v_mbcnt_lo_u32_b32 v1, -1, 0
	v_mbcnt_hi_u32_b32 v1, -1, v1
	s_nop 0
	v_add_u32_e32 v0, s0, v1
	v_writelane_b32 v238, s5, 1
	v_writelane_b32 v238, s0, 2
	s_movk_i32 s0, 0xc00
	v_cmp_gt_i32_e32 vcc, s0, v0
	s_and_saveexec_b64 s[0:1], vcc
	s_cbranch_execz .LBB13_3
	s_lshl_b32 s4, s3, 2
	s_and_b32 s4, s4, 0xffffff00
	s_add_i32 s4, s4, 0
	v_lshl_add_u32 v1, v1, 2, s4
	v_add_u32_e32 v0, 0xfffffe00, v0
	v_add_u32_e32 v1, 0x21000, v1
	s_mov_b64 s[4:5], 0
	v_mov_b32_e32 v2, 0
	s_movk_i32 s6, 0x9ff

; __device__ __forceinline__ void gmlp_phase(GM_LAS unsigned char* lds, int wid0, const pg8::Place& pl, const bf16_t* U, const bf16_t* VN, const bf16_t* GW  , const float* bs  , const float* gog  , bf16_t* Y, float* ssqy) {
;     ...
;     if (pl.rank + pl.nloc < 8 * nu) GM_LOAD(stB, uuB, pl.rank + pl.nloc);
.LBB13_799:
	s_load_dwordx2 s[2:3], s[12:13], 0x40
	s_nop 0
	s_load_dwordx2 s[12:13], s[12:13], 0x68
	s_add_i32 s16, s30, s41
	s_cmp_ge_i32 s16, s33
	s_cbranch_scc1 .LBB13_801
	s_ashr_i32 s17, s16, 3
	s_add_i32 s18, s31, s17
	s_ashr_i32 s19, s18, 31
	s_lshl_b32 s16, s16, 7
	s_lshl_b64 s[18:19], s[18:19], 7
	s_and_b32 s84, s16, 0x380
	s_add_u32 s16, s8, s84
	s_addc_u32 s17, s9, 0
	v_lshl_add_u64 v[12:13], s[16:17], 0, v[0:1]
	s_lshl_b32 s16, s14, 4
	s_ashr_i32 s17, s16, 31
	s_add_u32 s16, s18, s16
	s_addc_u32 s17, s19, s17
	v_or_b32_e32 v26, s16, v23
	v_mov_b32_e32 v27, s17
	v_ashrrev_i32_e32 v75, 31, v74
	v_lshlrev_b64 v[26:27], 10, v[26:27]
	v_lshl_add_u64 v[14:15], s[18:19], 0, v[72:73]
	v_lshl_add_u64 v[16:17], s[18:19], 0, v[74:75]
	v_lshl_add_u64 v[26:27], s[0:1], 0, v[26:27]
	v_lshlrev_b64 v[14:15], 10, v[14:15]
	v_lshlrev_b64 v[16:17], 10, v[16:17]
	v_lshl_add_u64 v[26:27], v[26:27], 0, s[84:85]
	v_mov_b32_e32 v21, v1
	v_lshl_add_u64 v[14:15], v[12:13], 0, v[14:15]
	v_lshl_add_u64 v[16:17], v[12:13], 0, v[16:17]
	v_lshl_add_u64 v[20:21], v[26:27], 0, v[20:21]
	global_load_dwordx4 v[12:15], v[14:15], off
	s_nop 0
	global_load_dwordx4 v[16:19], v[16:17], off
	s_nop 0
	global_load_dwordx2 v[140:141], v[20:21], off
	global_load_dwordx2 v[142:143], v[20:21], off offset:32
	global_load_dwordx2 v[144:145], v[20:21], off offset:64
	global_load_dwordx2 v[146:147], v[20:21], off offset:96

; __device__ __forceinline__ void gmlp_phase(GM_LAS unsigned char* lds, int wid0, const pg8::Place& pl, const bf16_t* U, const bf16_t* VN, const bf16_t* GW  , const float* bs  , const float* gog  , bf16_t* Y, float* ssqy) {
;     ...
;     for (int idx0 = pl.rank; idx0 < 8 * nu; idx0 += 2 * pl.nloc) {
;         GM_UNIT(stA, uuA, idx0);
;         if (idx0 + pl.nloc < 8 * nu) GM_UNIT(stB, uuB, idx0 + pl.nloc);
.LBB13_804:
	s_add_i32 s37, s37, s38
	s_andn2_b64 vcc, exec, s[26:27]
	s_cmp_eq_u32 s98, 0
	s_cbranch_scc1 .Lgm0_l10
	s_waitcnt vmcnt(16)
	s_branch .Lgm0_ld
.Lgm0_l10:
	s_waitcnt vmcnt(10)
.Lgm0_ld:
	v_mov_b64_e32 v[2:3], v[102:103]
	v_mov_b64_e32 v[106:107], v[100:101]
	v_mov_b64_e32 v[108:109], v[98:99]
	v_mov_b64_e32 v[110:111], v[96:97]
	s_mov_b32 s41, s40
	s_cbranch_vccz .LBB13_739
.LBB13_805:
	s_and_b32 s42, s41, 7
	s_cmp_eq_u32 s42, s39
	s_cbranch_scc1 .LBB13_807
	v_lshl_add_u32 v36, s42, 7, v76
	v_ashrrev_i32_e32 v37, 31, v36
	v_lshlrev_b64 v[20:21], 8, v[36:37]
	s_lshl_b32 s84, s42, 8
	v_lshl_add_u64 v[32:33], v[78:79], 0, v[20:21]
	v_lshl_add_u64 v[36:37], v[36:37], 2, s[2:3]
	v_lshl_add_u64 v[48:49], v[82:83], 0, s[84:85]
	global_load_dwordx4 v[20:23], v[32:33], off
	global_load_dwordx4 v[24:27], v[32:33], off offset:64
	global_load_dwordx4 v[28:31], v[32:33], off offset:128
	s_nop 0
	global_load_dwordx4 v[32:35], v[32:33], off offset:192
	s_mov_b32 s39, s42
	global_load_dword v88, v[36:37], off
	s_nop 0
	global_load_dwordx4 v[36:39], v[48:49], off
	global_load_dwordx4 v[40:43], v[48:49], off offset:64
	global_load_dwordx4 v[44:47], v[48:49], off offset:128
	s_nop 0
	global_load_dwordx4 v[48:51], v[48:49], off offset:192
	s_waitcnt vmcnt(0)
.LBB13_807:
	s_barrier
	s_nop 0
	ds_write_b128 v120, v[4:7]
	s_nop 0
	ds_write_b128 v121, v[8:11]
	s_add_i32 s40, s41, s34
	s_waitcnt lgkmcnt(0)
	s_barrier
	s_cmp_ge_i32 s40, s33
	s_cselect_b64 s[26:27], -1, 0
	s_and_b64 vcc, exec, s[26:27]
	v_lshlrev_b32_e32 v104, 1, v80
	s_nop 0
	v_mov_b64_e32 v[102:103], v[2:3]
	v_mov_b64_e32 v[100:101], v[106:107]
	v_mov_b64_e32 v[98:99], v[108:109]
	v_mov_b64_e32 v[96:97], v[110:111]
	s_cbranch_vccnz .LBB13_809
	s_ashr_i32 s8, s40, 3
	s_add_i32 s8, s8, s31
	s_ashr_i32 s9, s8, 31
	s_lshl_b64 s[8:9], s[8:9], 7
	s_add_i32 s10, s38, s37
	v_lshl_add_u64 v[52:53], s[8:9], 0, v[76:77]
	s_and_b32 s10, s10, 0x1c0
	v_lshlrev_b64 v[52:53], 10, v[52:53]
	s_lshl_b32 s84, s10, 1
	v_lshl_add_u64 v[6:7], s[8:9], 0, v[72:73]
	v_lshl_add_u64 v[8:9], s[8:9], 0, v[74:75]
	v_lshl_add_u64 v[52:53], s[0:1], 0, v[52:53]
	v_lshl_add_u64 v[4:5], v[84:85], 0, s[84:85]
	v_lshlrev_b64 v[6:7], 10, v[6:7]
	v_lshlrev_b64 v[8:9], 10, v[8:9]
	v_lshl_add_u64 v[52:53], v[52:53], 0, s[84:85]
	v_mov_b32_e32 v105, v1
	v_lshl_add_u64 v[6:7], v[4:5], 0, v[6:7]
	v_lshl_add_u64 v[8:9], v[4:5], 0, v[8:9]
	v_lshl_add_u64 v[52:53], v[52:53], 0, v[104:105]
	global_load_dwordx4 v[4:7], v[6:7], off
	s_nop 0
	global_load_dwordx4 v[8:11], v[8:9], off
	s_nop 0
	global_load_dwordx2 v[96:97], v[52:53], off
	global_load_dwordx2 v[98:99], v[52:53], off offset:32
	global_load_dwordx2 v[100:101], v[52:53], off offset:64
	global_load_dwordx2 v[102:103], v[52:53], off offset:96

.LBB13_819:
	s_barrier
	s_and_b64 vcc, exec, s[26:27]
	s_cbranch_vccnz .Lgm0_b10
	s_waitcnt vmcnt(16)
	s_branch .Lgm0_bd

.Lgm0_bd:
	v_mov_b64_e32 v[94:95], v[140:141]
	v_mov_b64_e32 v[92:93], v[142:143]
	v_mov_b64_e32 v[90:91], v[144:145]
	v_mov_b64_e32 v[86:87], v[146:147]
	ds_write_b128 v120, v[12:15]
	ds_write_b128 v121, v[16:19]
	s_waitcnt lgkmcnt(0)
	s_barrier
	s_add_i32 s41, s35, s41
	s_cmp_ge_i32 s41, s33
	s_cselect_b32 s98, 0, 1
	v_mov_b64_e32 v[114:115], v[86:87]
	v_mov_b64_e32 v[112:113], v[90:91]
	v_mov_b64_e32 v[70:71], v[92:93]
	v_mov_b64_e32 v[68:69], v[94:95]
	s_cbranch_scc1 .LBB13_821
	s_ashr_i32 s41, s41, 3
	s_add_i32 s42, s41, s31
	s_ashr_i32 s43, s42, 31
	s_add_i32 s41, s36, s37
	s_lshl_b64 s[42:43], s[42:43], 7
	s_and_b32 s41, s41, 0x1c0
	s_lshl_b32 s84, s41, 1
	v_lshl_add_u64 v[12:13], s[42:43], 0, v[72:73]
	v_lshl_add_u64 v[14:15], s[42:43], 0, v[74:75]
	v_lshl_add_u64 v[2:3], v[84:85], 0, s[84:85]
	v_lshlrev_b64 v[12:13], 10, v[12:13]
	v_lshlrev_b64 v[14:15], 10, v[14:15]
	v_lshl_add_u64 v[12:13], v[2:3], 0, v[12:13]
	v_lshl_add_u64 v[2:3], v[2:3], 0, v[14:15]
	global_load_dwordx4 v[12:15], v[12:13], off
	s_nop 0
	global_load_dwordx4 v[16:19], v[2:3], off
	v_lshl_add_u64 v[2:3], s[42:43], 0, v[76:77]
	v_lshlrev_b64 v[2:3], 10, v[2:3]
	v_lshl_add_u64 v[2:3], s[0:1], 0, v[2:3]
	v_lshl_add_u64 v[2:3], v[2:3], 0, s[84:85]
	v_mov_b32_e32 v105, v1
	v_lshl_add_u64 v[2:3], v[2:3], 0, v[104:105]
	global_load_dwordx2 v[140:141], v[2:3], off
	global_load_dwordx2 v[142:143], v[2:3], off offset:32
	global_load_dwordx2 v[144:145], v[2:3], off offset:64
	global_load_dwordx2 v[146:147], v[2:3], off offset:96

; __device__ __forceinline__ void gmlp_phase(GM_LAS unsigned char* lds, int wid0, const pg8::Place& pl, const bf16_t* U, const bf16_t* VN, const bf16_t* GW  , const float* bs  , const float* gog  , bf16_t* Y, float* ssqy) {
;     ...
;     if (pl.rank + pl.nloc < 8 * nu) GM_LOAD(stB, uuB, pl.rank + pl.nloc);
.LBB13_1777:
	s_load_dwordx2 s[12:13], s[10:11], 0x40
	s_nop 0
	s_load_dwordx2 s[10:11], s[10:11], 0x68
	s_add_i32 s16, s30, s41
	s_cmp_ge_i32 s16, s33
	s_cbranch_scc1 .LBB13_1779
	s_ashr_i32 s17, s16, 3
	s_add_i32 s18, s31, s17
	s_ashr_i32 s19, s18, 31
	s_lshl_b32 s16, s16, 7
	s_lshl_b64 s[18:19], s[18:19], 7
	s_and_b32 s84, s16, 0x380
	s_add_u32 s16, s8, s84
	s_addc_u32 s17, s9, 0
	v_lshl_add_u64 v[12:13], s[16:17], 0, v[0:1]
	s_lshl_b32 s16, s14, 4
	s_ashr_i32 s17, s16, 31
	s_add_u32 s16, s18, s16
	s_addc_u32 s17, s19, s17
	v_or_b32_e32 v26, s16, v23
	v_mov_b32_e32 v27, s17
	v_ashrrev_i32_e32 v75, 31, v74
	v_lshlrev_b64 v[26:27], 10, v[26:27]
	v_lshl_add_u64 v[14:15], s[18:19], 0, v[72:73]
	v_lshl_add_u64 v[16:17], s[18:19], 0, v[74:75]
	v_lshl_add_u64 v[26:27], s[0:1], 0, v[26:27]
	v_lshlrev_b64 v[14:15], 10, v[14:15]
	v_lshlrev_b64 v[16:17], 10, v[16:17]
	v_lshl_add_u64 v[26:27], v[26:27], 0, s[84:85]
	v_mov_b32_e32 v21, v1
	v_lshl_add_u64 v[14:15], v[12:13], 0, v[14:15]
	v_lshl_add_u64 v[16:17], v[12:13], 0, v[16:17]
	v_lshl_add_u64 v[20:21], v[26:27], 0, v[20:21]
	global_load_dwordx4 v[12:15], v[14:15], off
	s_nop 0
	global_load_dwordx4 v[16:19], v[16:17], off
	s_nop 0
	global_load_dwordx2 v[140:141], v[20:21], off
	global_load_dwordx2 v[142:143], v[20:21], off offset:32
	global_load_dwordx2 v[144:145], v[20:21], off offset:64
	global_load_dwordx2 v[146:147], v[20:21], off offset:96

.LBB13_1783:
	s_and_b32 s42, s41, 7
	s_cmp_eq_u32 s42, s39
	s_cbranch_scc1 .LBB13_1785
	v_lshl_add_u32 v36, s42, 7, v76
	v_ashrrev_i32_e32 v37, 31, v36
	v_lshlrev_b64 v[20:21], 8, v[36:37]
	s_lshl_b32 s84, s42, 8
	v_lshl_add_u64 v[32:33], v[78:79], 0, v[20:21]
	v_lshl_add_u64 v[36:37], v[36:37], 2, s[4:5]
	v_lshl_add_u64 v[48:49], v[82:83], 0, s[84:85]
	global_load_dwordx4 v[20:23], v[32:33], off
	global_load_dwordx4 v[24:27], v[32:33], off offset:64
	global_load_dwordx4 v[28:31], v[32:33], off offset:128
	s_nop 0
	global_load_dwordx4 v[32:35], v[32:33], off offset:192
	s_mov_b32 s39, s42
	global_load_dword v88, v[36:37], off
	s_nop 0
	global_load_dwordx4 v[36:39], v[48:49], off offset:2048
	global_load_dwordx4 v[40:43], v[48:49], off offset:2112
	global_load_dwordx4 v[44:47], v[48:49], off offset:2176
	s_nop 0
	global_load_dwordx4 v[48:51], v[48:49], off offset:2240
	s_waitcnt vmcnt(0)

; __global__ void __launch_bounds__(NWAVES * 64, 2) mk_fwd(Args args) {
	.amdhsa_kernel _Z6mk_fwd4Args
		.amdhsa_group_segment_fixed_size 0
		.amdhsa_private_segment_fixed_size 0
		.amdhsa_kernarg_size 448
		.amdhsa_user_sgpr_count 2
		.amdhsa_user_sgpr_dispatch_ptr 0
		.amdhsa_user_sgpr_queue_ptr 0
		.amdhsa_user_sgpr_kernarg_segment_ptr 1
		.amdhsa_user_sgpr_dispatch_id 0
		.amdhsa_user_sgpr_kernarg_preload_length 0
		.amdhsa_user_sgpr_kernarg_preload_offset 0
		.amdhsa_user_sgpr_private_segment_size 0
		.amdhsa_uses_dynamic_stack 0
		.amdhsa_enable_private_segment 0
		.amdhsa_system_sgpr_workgroup_id_x 1
		.amdhsa_system_sgpr_workgroup_id_y 0
		.amdhsa_system_sgpr_workgroup_id_z 0
		.amdhsa_system_sgpr_workgroup_info 0
		.amdhsa_system_vgpr_workitem_id 0
		.amdhsa_next_free_vgpr 256
		.amdhsa_next_free_sgpr 99
		.amdhsa_accum_offset 256
		.amdhsa_reserve_vcc 1
		.amdhsa_float_round_mode_32 0
		.amdhsa_float_round_mode_16_64 0
		.amdhsa_float_denorm_mode_32 3
		.amdhsa_float_denorm_mode_16_64 3
		.amdhsa_dx10_clamp 1
		.amdhsa_ieee_mode 1
		.amdhsa_fp16_overflow 0
		.amdhsa_tg_split 0
		.amdhsa_exception_fp_ieee_invalid_op 0
		.amdhsa_exception_fp_denorm_src 0
		.amdhsa_exception_fp_ieee_div_zero 0
		.amdhsa_exception_fp_ieee_overflow 0
		.amdhsa_exception_fp_ieee_underflow 0
		.amdhsa_exception_fp_ieee_inexact 0
		.amdhsa_exception_int_div_zero 0
	.end_amdhsa_kernel

; __device__ __forceinline__ bf16_t f2bf(float f) { unsigned u = __float_as_uint(f); return (bf16_t)((u + 0x7fffu + ((u >> 16) & 1u)) >> 16); }
; __global__ void k_rope_table(const int* pos, float* rope) {
;     const int idx = blockIdx.x * blockDim.x + threadIdx.x; if (idx >= T * 16) return;
;     const int t = idx >> 4, i = idx & 15;
;     const float freq = powf(10000.0f, -(float)(2 * i) / 32.0f);
;     const float ang = (float)pos[t] * freq;
;     rope[t * 32 + i] = cosf(ang); rope[t * 32 + 16 + i] = sinf(ang);
; }
; __global__ void k_prep_w(const float* W, int K, int N, bf16_t* out, int Nphys, int mode) {
;     const size_t idx = (size_t)blockIdx.x * blockDim.x + threadIdx.x; if (idx >= (size_t)Nphys * K) return;
;     const int p = (int)(idx / K), k = (int)(idx % K);
;     const int s = mode == 1 ? win_src(p) : p;
;     out[idx] = (s >= 0 && s < N) ? f2bf(W[(size_t)k * N + s]) : (bf16_t)0;
; }
amdhsa.kernels:
  - .agpr_count:     0
    .args:
      - .address_space:  global
        .offset:         0
        .size:           8
        .value_kind:     global_buffer
      - .address_space:  global
        .offset:         8
        .size:           8
        .value_kind:     global_buffer
      - .offset:         16
        .size:           4
        .value_kind:     hidden_block_count_x
      - .offset:         20
        .size:           4
        .value_kind:     hidden_block_count_y
      - .offset:         24
        .size:           4
        .value_kind:     hidden_block_count_z
      - .offset:         28
        .size:           2
        .value_kind:     hidden_group_size_x
      - .offset:         30
        .size:           2
        .value_kind:     hidden_group_size_y
      - .offset:         32
        .size:           2
        .value_kind:     hidden_group_size_z
      - .offset:         34
        .size:           2
        .value_kind:     hidden_remainder_x
      - .offset:         36
        .size:           2
        .value_kind:     hidden_remainder_y
      - .offset:         38
        .size:           2
        .value_kind:     hidden_remainder_z
      - .offset:         56
        .size:           8
        .value_kind:     hidden_global_offset_x
      - .offset:         64
        .size:           8
        .value_kind:     hidden_global_offset_y
      - .offset:         72
        .size:           8
        .value_kind:     hidden_global_offset_z
      - .offset:         80
        .size:           2
        .value_kind:     hidden_grid_dims
    .group_segment_fixed_size: 0
    .kernarg_segment_align: 8
    .kernarg_segment_size: 272
    .language:       OpenCL C
    .language_version:
      - 2
      - 0
    .max_flat_workgroup_size: 1024
    .name:           _Z12k_rope_tablePKiPf
    .private_segment_fixed_size: 0
    .sgpr_count:     18
    .sgpr_spill_count: 0
    .symbol:         _Z12k_rope_tablePKiPf.kd
    .uniform_work_group_size: 1
    .uses_dynamic_stack: false
    .vgpr_count:     22
    .vgpr_spill_count: 0
    .wavefront_size: 64
  - .agpr_count:     0
    .args:
      - .address_space:  global
        .offset:         0
        .size:           8
        .value_kind:     global_buffer
      - .offset:         8
        .size:           4
        .value_kind:     by_value
      - .offset:         12
        .size:           4
        .value_kind:     by_value
      - .address_space:  global
        .offset:         16
        .size:           8
        .value_kind:     global_buffer
      - .offset:         24
        .size:           4
        .value_kind:     by_value
      - .offset:         28
        .size:           4
        .value_kind:     by_value
      - .offset:         32
        .size:           4
        .value_kind:     hidden_block_count_x
      - .offset:         36
        .size:           4
        .value_kind:     hidden_block_count_y
      - .offset:         40
        .size:           4
        .value_kind:     hidden_block_count_z
      - .offset:         44
        .size:           2
        .value_kind:     hidden_group_size_x
      - .offset:         46
        .size:           2
        .value_kind:     hidden_group_size_y
      - .offset:         48
        .size:           2
        .value_kind:     hidden_group_size_z
      - .offset:         50
        .size:           2
        .value_kind:     hidden_remainder_x
      - .offset:         52
        .size:           2
        .value_kind:     hidden_remainder_y
      - .offset:         54
        .size:           2
        .value_kind:     hidden_remainder_z
      - .offset:         72
        .size:           8
        .value_kind:     hidden_global_offset_x
      - .offset:         80
        .size:           8
        .value_kind:     hidden_global_offset_y
      - .offset:         88
        .size:           8
        .value_kind:     hidden_global_offset_z
      - .offset:         96
        .size:           2
        .value_kind:     hidden_grid_dims
    .group_segment_fixed_size: 0
    .kernarg_segment_align: 8
    .kernarg_segment_size: 288
    .language:       OpenCL C
    .language_version:
      - 2
      - 0
    .max_flat_workgroup_size: 1024
    .name:           _Z8k_prep_wPKfiiPtii
    .private_segment_fixed_size: 0
    .sgpr_count:     24
    .sgpr_spill_count: 0
    .symbol:         _Z8k_prep_wPKfiiPtii.kd
    .uniform_work_group_size: 1
    .uses_dynamic_stack: false
    .vgpr_count:     11
    .vgpr_spill_count: 0
    .wavefront_size: 64
; __global__ void k_prep_wup(const float* wuq, const float* wukv, bf16_t* out) {
;     const int idx = blockIdx.x * blockDim.x + threadIdx.x; if (idx >= NUP * KUP) return;
;     const int p = idx / KUP, k = idx % KUP; float v = 0.f;
;     if (p < 768) { if (k < 256) v = wuq[(size_t)k * 768 + wup_qcol(p)]; }
;     else { if (k >= 256) v = wukv[(size_t)(k - 256) * 1024 + (p - 768)]; }
;     out[idx] = f2bf(v);
; }
; __global__ void k_prep_gw(const float* ws, bf16_t* gw) {
;     const int idx = blockIdx.x * blockDim.x + threadIdx.x; if (idx >= DEPTH * NGRP * CHUNK * CHUNK) return;
;     const int s = idx & 127, t = (idx >> 7) & 127;
;     gw[idx] = (s <= t) ? f2bf(ws[idx]) : (bf16_t)0;
; }
; __global__ __launch_bounds__(512) void k_smallm(const float* in, int in_stride, int act, const float* W, int ldw, int N, int mode, const float* bias, float* out, int out_stride, int Nphys) {
;     __shared__ float sin_[1024 * 16];
;     __shared__ float red[8 * 64 * 16];
;     const int tid = threadIdx.x, lane = tid & 63, wave = tid >> 6;
;     for (int e = tid; e < 16 * 1024; e += 512) { const int b = e >> 10, k = e & 1023; float v = in[(size_t)b * in_stride + k]; if (act) v = v / (1.f + __expf(-v)); sin_[k * 16 + b] = v; }
;     __syncthreads();
;     const int p = blockIdx.x * 64 + lane; const int s = (p < Nphys) ? (mode == 1 ? win_src(p) : p) : -1; const bool ok = (s >= 0 && s < N);
;     float acc[16];
; #pragma unroll
;     for (int b = 0; b < 16; ++b) acc[b] = 0.f;
;     for (int k = wave * 128; k < wave * 128 + 128; ++k) {
;         const float w = ok ? W[(size_t)k * ldw + s] : 0.f;
;         const f32x4* sp = (const f32x4*)(sin_ + k * 16);
; #pragma unroll
;         for (int q = 0; q < 4; ++q) { const f32x4 v = sp[q]; acc[4 * q] += v[0] * w; acc[4 * q + 1] += v[1] * w; acc[4 * q + 2] += v[2] * w; acc[4 * q + 3] += v[3] * w; }
;     }
; #pragma unroll
;     for (int b = 0; b < 16; ++b) red[(wave * 64 + lane) * 16 + b] = acc[b];
;     __syncthreads();
;     for (int e = tid; e < 64 * 16; e += 512) { const int l = e >> 4, b = e & 15; float sum = 0.f;
; #pragma unroll
;         for (int w = 0; w < 8; ++w) sum += red[(w * 64 + l) * 16 + b];
;         const int pp = blockIdx.x * 64 + l; if (pp < Nphys) out[(size_t)b * out_stride + pp] = sum + (bias ? bias[pp] : 0.f); }
; }
  - .agpr_count:     0
    .args:
      - .address_space:  global
        .offset:         0
        .size:           8
        .value_kind:     global_buffer
      - .address_space:  global
        .offset:         8
        .size:           8
        .value_kind:     global_buffer
      - .address_space:  global
        .offset:         16
        .size:           8
        .value_kind:     global_buffer
      - .offset:         24
        .size:           4
        .value_kind:     hidden_block_count_x
      - .offset:         28
        .size:           4
        .value_kind:     hidden_block_count_y
      - .offset:         32
        .size:           4
        .value_kind:     hidden_block_count_z
      - .offset:         36
        .size:           2
        .value_kind:     hidden_group_size_x
      - .offset:         38
        .size:           2
        .value_kind:     hidden_group_size_y
      - .offset:         40
        .size:           2
        .value_kind:     hidden_group_size_z
      - .offset:         42
        .size:           2
        .value_kind:     hidden_remainder_x
      - .offset:         44
        .size:           2
        .value_kind:     hidden_remainder_y
      - .offset:         46
        .size:           2
        .value_kind:     hidden_remainder_z
      - .offset:         64
        .size:           8
        .value_kind:     hidden_global_offset_x
      - .offset:         72
        .size:           8
        .value_kind:     hidden_global_offset_y
      - .offset:         80
        .size:           8
        .value_kind:     hidden_global_offset_z
      - .offset:         88
        .size:           2
        .value_kind:     hidden_grid_dims
    .group_segment_fixed_size: 0
    .kernarg_segment_align: 8
    .kernarg_segment_size: 280
    .language:       OpenCL C
    .language_version:
      - 2
      - 0
    .max_flat_workgroup_size: 1024
    .name:           _Z10k_prep_wupPKfS0_Pt
    .private_segment_fixed_size: 0
    .sgpr_count:     16
    .sgpr_spill_count: 0
    .symbol:         _Z10k_prep_wupPKfS0_Pt.kd
    .uniform_work_group_size: 1
    .uses_dynamic_stack: false
    .vgpr_count:     8
    .vgpr_spill_count: 0
    .wavefront_size: 64
  - .agpr_count:     0
    .args:
      - .address_space:  global
        .offset:         0
        .size:           8
        .value_kind:     global_buffer
      - .address_space:  global
        .offset:         8
        .size:           8
        .value_kind:     global_buffer
      - .offset:         16
        .size:           4
        .value_kind:     hidden_block_count_x
      - .offset:         20
        .size:           4
        .value_kind:     hidden_block_count_y
      - .offset:         24
        .size:           4
        .value_kind:     hidden_block_count_z
      - .offset:         28
        .size:           2
        .value_kind:     hidden_group_size_x
      - .offset:         30
        .size:           2
        .value_kind:     hidden_group_size_y
      - .offset:         32
        .size:           2
        .value_kind:     hidden_group_size_z
      - .offset:         34
        .size:           2
        .value_kind:     hidden_remainder_x
      - .offset:         36
        .size:           2
        .value_kind:     hidden_remainder_y
      - .offset:         38
        .size:           2
        .value_kind:     hidden_remainder_z
      - .offset:         56
        .size:           8
        .value_kind:     hidden_global_offset_x
      - .offset:         64
        .size:           8
        .value_kind:     hidden_global_offset_y
      - .offset:         72
        .size:           8
        .value_kind:     hidden_global_offset_z
      - .offset:         80
        .size:           2
        .value_kind:     hidden_grid_dims
    .group_segment_fixed_size: 0
    .kernarg_segment_align: 8
    .kernarg_segment_size: 272
    .language:       OpenCL C
    .language_version:
      - 2
      - 0
    .max_flat_workgroup_size: 1024
    .name:           _Z9k_prep_gwPKfPt
    .private_segment_fixed_size: 0
    .sgpr_count:     12
    .sgpr_spill_count: 0
    .symbol:         _Z9k_prep_gwPKfPt.kd
    .uniform_work_group_size: 1
    .uses_dynamic_stack: false
    .vgpr_count:     6
    .vgpr_spill_count: 0
    .wavefront_size: 64
  - .agpr_count:     0
    .args:
      - .address_space:  global
        .offset:         0
        .size:           8
        .value_kind:     global_buffer
      - .offset:         8
        .size:           4
        .value_kind:     by_value
      - .offset:         12
        .size:           4
        .value_kind:     by_value
      - .address_space:  global
        .offset:         16
        .size:           8
        .value_kind:     global_buffer
      - .offset:         24
        .size:           4
        .value_kind:     by_value
      - .offset:         28
        .size:           4
        .value_kind:     by_value
      - .offset:         32
        .size:           4
        .value_kind:     by_value
      - .address_space:  global
        .offset:         40
        .size:           8
        .value_kind:     global_buffer
      - .address_space:  global
        .offset:         48
        .size:           8
        .value_kind:     global_buffer
      - .offset:         56
        .size:           4
        .value_kind:     by_value
      - .offset:         60
        .size:           4
        .value_kind:     by_value
    .group_segment_fixed_size: 98304
    .kernarg_segment_align: 8
    .kernarg_segment_size: 64
    .language:       OpenCL C
    .language_version:
      - 2
      - 0
    .max_flat_workgroup_size: 512
    .name:           _Z8k_smallmPKfiiS0_iiiS0_Pfii
    .private_segment_fixed_size: 0
    .sgpr_count:     20
    .sgpr_spill_count: 0
    .symbol:         _Z8k_smallmPKfiiS0_iiiS0_Pfii.kd
    .uniform_work_group_size: 1
    .uses_dynamic_stack: false
    .vgpr_count:     38
    .vgpr_spill_count: 0
    .wavefront_size: 64
; __global__ __launch_bounds__(256) void k_modx(const float* x, const float* g, const float* sc  , int sc_stride, bf16_t* A, float* ssq) {
;     const int row = blockIdx.x * 4 + (threadIdx.x >> 6), lane = threadIdx.x & 63; if (row >= T) return;
;     const int b = row / SEQ; const f32x4* xr = (const f32x4*)(x + (size_t)row * DM); float s = 0.f;
; #pragma unroll
;     for (int j = 0; j < 4; ++j) { const f32x4 v = xr[lane + 64 * j]; s += v[0] * v[0] + v[1] * v[1] + v[2] * v[2] + v[3] * v[3];
;         const int c = 4 * (lane + 64 * j); const f32x4 gv = *(const f32x4*)(g + c), sv = *(const f32x4*)(sc + (size_t)b * sc_stride + c);
;         unsigned lo = f2bf(v[0] * gv[0] * (1.f + sv[0])) | ((unsigned)f2bf(v[1] * gv[1] * (1.f + sv[1])) << 16);
;         unsigned hi = f2bf(v[2] * gv[2] * (1.f + sv[2])) | ((unsigned)f2bf(v[3] * gv[3] * (1.f + sv[3])) << 16);
;         *(uint2*)(A + (size_t)row * DM + c) = make_uint2(lo, hi); }
;     s = wave_sum(s);
;     if (lane < 16) ssq[(size_t)row * 16 + lane] = (lane == 0) ? s : 0.f;
; }
; __global__ __launch_bounds__(256) void k_final(const float* x, const float* g, float* out) {
;     const int row = blockIdx.x * 4 + (threadIdx.x >> 6), lane = threadIdx.x & 63; if (row >= T) return;
;     const f32x4* xr = (const f32x4*)(x + (size_t)row * DM); f32x4 v[4]; float s = 0.f;
; #pragma unroll
;     for (int j = 0; j < 4; ++j) { v[j] = xr[lane + 64 * j]; s += v[j][0] * v[j][0] + v[j][1] * v[j][1] + v[j][2] * v[j][2] + v[j][3] * v[j][3]; }
;     const float rstd = rsqrtf(wave_sum(s) * (1.f / DM) + EPS);
; #pragma unroll
;     for (int j = 0; j < 4; ++j) { const int c = 4 * (lane + 64 * j); const f32x4 gv = *(const f32x4*)(g + c); *(f32x4*)(out + (size_t)row * DM + c) = v[j] * rstd * gv; }
; }
; __global__ __launch_bounds__(256) void k_vn(const float* GV, bf16_t* VN) {
;     const int w = blockIdx.x * 4 + (threadIdx.x >> 6), lane = threadIdx.x & 63; if (w >= T * NGRP) return;
;     const int row = w >> 3, g = w & 7; const float v = GV[(size_t)row * 512 + g * 64 + lane];
;     const float mu = wave_sum(v) * (1.f / 64); const float d = v - mu; const float var = wave_sum(d * d) * (1.f / 64);
;     VN[(size_t)row * 512 + g * 64 + lane] = f2bf(d * rsqrtf(var + EPS));
; }
; __global__ __launch_bounds__(256) void k_lat(const float* ZL, const float* gq, const float* gkv, const float* rope, bf16_t* CQKV, float* ssqq, bf16_t* KR) {
  - .agpr_count:     0
    .args:
      - .address_space:  global
        .offset:         0
        .size:           8
        .value_kind:     global_buffer
      - .address_space:  global
        .offset:         8
        .size:           8
        .value_kind:     global_buffer
      - .address_space:  global
        .offset:         16
        .size:           8
        .value_kind:     global_buffer
      - .offset:         24
        .size:           4
        .value_kind:     by_value
      - .address_space:  global
        .offset:         32
        .size:           8
        .value_kind:     global_buffer
      - .address_space:  global
        .offset:         40
        .size:           8
        .value_kind:     global_buffer
    .group_segment_fixed_size: 0
    .kernarg_segment_align: 8
    .kernarg_segment_size: 48
    .language:       OpenCL C
    .language_version:
      - 2
      - 0
    .max_flat_workgroup_size: 256
    .name:           _Z6k_modxPKfS0_S0_iPtPf
    .private_segment_fixed_size: 0
    .sgpr_count:     19
    .sgpr_spill_count: 0
    .symbol:         _Z6k_modxPKfS0_S0_iPtPf.kd
    .uniform_work_group_size: 1
    .uses_dynamic_stack: false
    .vgpr_count:     40
    .vgpr_spill_count: 0
    .wavefront_size: 64
  - .agpr_count:     0
    .args:
      - .address_space:  global
        .offset:         0
        .size:           8
        .value_kind:     global_buffer
      - .address_space:  global
        .offset:         8
        .size:           8
        .value_kind:     global_buffer
      - .address_space:  global
        .offset:         16
        .size:           8
        .value_kind:     global_buffer
    .group_segment_fixed_size: 0
    .kernarg_segment_align: 8
    .kernarg_segment_size: 24
    .language:       OpenCL C
    .language_version:
      - 2
      - 0
    .max_flat_workgroup_size: 256
    .name:           _Z7k_finalPKfS0_Pf
    .private_segment_fixed_size: 0
    .sgpr_count:     14
    .sgpr_spill_count: 0
    .symbol:         _Z7k_finalPKfS0_Pf.kd
    .uniform_work_group_size: 1
    .uses_dynamic_stack: false
    .vgpr_count:     43
    .vgpr_spill_count: 0
    .wavefront_size: 64
  - .agpr_count:     0
    .args:
      - .address_space:  global
        .offset:         0
        .size:           8
        .value_kind:     global_buffer
      - .address_space:  global
        .offset:         8
        .size:           8
        .value_kind:     global_buffer
    .group_segment_fixed_size: 0
    .kernarg_segment_align: 8
    .kernarg_segment_size: 16
    .language:       OpenCL C
    .language_version:
      - 2
      - 0
    .max_flat_workgroup_size: 256
    .name:           _Z4k_vnPKfPt
    .private_segment_fixed_size: 0
    .sgpr_count:     10
    .sgpr_spill_count: 0
    .symbol:         _Z4k_vnPKfPt.kd
    .uniform_work_group_size: 1
    .uses_dynamic_stack: false
    .vgpr_count:     13
    .vgpr_spill_count: 0
    .wavefront_size: 64
  - .agpr_count:     0
    .args:
      - .address_space:  global
        .offset:         0
        .size:           8
        .value_kind:     global_buffer
      - .address_space:  global
        .offset:         8
        .size:           8
        .value_kind:     global_buffer
      - .address_space:  global
        .offset:         16
        .size:           8
        .value_kind:     global_buffer
      - .address_space:  global
        .offset:         24
        .size:           8
        .value_kind:     global_buffer
      - .address_space:  global
        .offset:         32
        .size:           8
        .value_kind:     global_buffer
      - .address_space:  global
        .offset:         40
        .size:           8
        .value_kind:     global_buffer
      - .address_space:  global
        .offset:         48
        .size:           8
        .value_kind:     global_buffer
    .group_segment_fixed_size: 0
    .kernarg_segment_align: 8
    .kernarg_segment_size: 56
    .language:       OpenCL C
    .language_version:
      - 2
      - 0
    .max_flat_workgroup_size: 256
    .name:           _Z5k_latPKfS0_S0_S0_PtPfS1_
    .private_segment_fixed_size: 0
    .sgpr_count:     26
    .sgpr_spill_count: 0
    .symbol:         _Z5k_latPKfS0_S0_S0_PtPfS1_.kd
    .uniform_work_group_size: 1
    .uses_dynamic_stack: false
    .vgpr_count:     32
    .vgpr_spill_count: 0
    .wavefront_size: 64
  - .agpr_count:     0
    .args:
      - .address_space:  global
        .offset:         0
        .size:           8
        .value_kind:     global_buffer
      - .address_space:  global
        .offset:         8
        .size:           8
        .value_kind:     global_buffer
      - .address_space:  global
        .offset:         16
        .size:           8
        .value_kind:     global_buffer
      - .offset:         24
        .size:           4
        .value_kind:     hidden_block_count_x
      - .offset:         28
        .size:           4
        .value_kind:     hidden_block_count_y
      - .offset:         32
        .size:           4
        .value_kind:     hidden_block_count_z
      - .offset:         36
        .size:           2
        .value_kind:     hidden_group_size_x
      - .offset:         38
        .size:           2
        .value_kind:     hidden_group_size_y
      - .offset:         40
        .size:           2
        .value_kind:     hidden_group_size_z
      - .offset:         42
        .size:           2
        .value_kind:     hidden_remainder_x
      - .offset:         44
        .size:           2
        .value_kind:     hidden_remainder_y
      - .offset:         46
        .size:           2
        .value_kind:     hidden_remainder_z
      - .offset:         64
        .size:           8
        .value_kind:     hidden_global_offset_x
      - .offset:         72
        .size:           8
        .value_kind:     hidden_global_offset_y
      - .offset:         80
        .size:           8
        .value_kind:     hidden_global_offset_z
      - .offset:         88
        .size:           2
        .value_kind:     hidden_grid_dims
    .group_segment_fixed_size: 0
    .kernarg_segment_align: 8
    .kernarg_segment_size: 280
    .language:       OpenCL C
    .language_version:
      - 2
      - 0
    .max_flat_workgroup_size: 1024
    .name:           _Z8k_rope_qPKfS0_Pt
    .private_segment_fixed_size: 0
    .sgpr_count:     14
    .sgpr_spill_count: 0
    .symbol:         _Z8k_rope_qPKfS0_Pt.kd
    .uniform_work_group_size: 1
    .uses_dynamic_stack: false
    .vgpr_count:     14
    .vgpr_spill_count: 0
    .wavefront_size: 64
; __device__ __forceinline__ bf16_t f2bf(float f) { unsigned u = __float_as_uint(f); return (bf16_t)((u + 0x7fffu + ((u >> 16) & 1u)) >> 16); }
; __device__ __forceinline__ float bf2f(bf16_t h) { return __uint_as_float(((unsigned)h) << 16); }
; __global__ __launch_bounds__(512) void k_gmlp_naive(const bf16_t* U, const bf16_t* VN, const bf16_t* GW  , const float* bs  , const float* gog, bf16_t* Y, float* ssqy) {
;     const int row = blockIdx.x, g = threadIdx.x >> 6, d = threadIdx.x & 63, c = g * 64 + d;
;     const int tt = row & 127, t0 = row - tt;
;     const bf16_t* w = GW + ((size_t)g * CHUNK + tt) * CHUNK; float sum = 0.f;
;     for (int s = 0; s <= tt; ++s) sum += bf2f(w[s]) * bf2f(VN[(size_t)(t0 + s) * 512 + c]);
;     const float y = bf2f(U[(size_t)row * 512 + c]) * (sum + bs[g * CHUNK + tt]);
;     Y[(size_t)row * DM + c] = f2bf(y * gog[c]);
;     const float q = wave_sum(y * y); if (d == 0) ssqy[(size_t)row * 16 + g] = q;
; }
; __global__ __launch_bounds__(64) void k_attn_naive(const bf16_t* Q, const bf16_t* KN, const bf16_t* KR, const bf16_t* V, const float* goa, bf16_t* Y, float* ssqy) {
  - .agpr_count:     0
    .args:
      - .address_space:  global
        .offset:         0
        .size:           8
        .value_kind:     global_buffer
      - .address_space:  global
        .offset:         8
        .size:           8
        .value_kind:     global_buffer
      - .address_space:  global
        .offset:         16
        .size:           8
        .value_kind:     global_buffer
      - .address_space:  global
        .offset:         24
        .size:           8
        .value_kind:     global_buffer
      - .address_space:  global
        .offset:         32
        .size:           8
        .value_kind:     global_buffer
      - .address_space:  global
        .offset:         40
        .size:           8
        .value_kind:     global_buffer
      - .address_space:  global
        .offset:         48
        .size:           8
        .value_kind:     global_buffer
    .group_segment_fixed_size: 0
    .kernarg_segment_align: 8
    .kernarg_segment_size: 56
    .language:       OpenCL C
    .language_version:
      - 2
      - 0
    .max_flat_workgroup_size: 512
    .name:           _Z12k_gmlp_naivePKtS0_S0_PKfS2_PtPf
    .private_segment_fixed_size: 0
    .sgpr_count:     28
    .sgpr_spill_count: 0
    .symbol:         _Z12k_gmlp_naivePKtS0_S0_PKfS2_PtPf.kd
    .uniform_work_group_size: 1
    .uses_dynamic_stack: false
    .vgpr_count:     12
    .vgpr_spill_count: 0
    .wavefront_size: 64
  - .agpr_count:     0
    .args:
      - .address_space:  global
        .offset:         0
        .size:           8
        .value_kind:     global_buffer
      - .address_space:  global
        .offset:         8
        .size:           8
        .value_kind:     global_buffer
      - .address_space:  global
        .offset:         16
        .size:           8
        .value_kind:     global_buffer
      - .address_space:  global
        .offset:         24
        .size:           8
        .value_kind:     global_buffer
      - .address_space:  global
        .offset:         32
        .size:           8
        .value_kind:     global_buffer
      - .address_space:  global
        .offset:         40
        .size:           8
        .value_kind:     global_buffer
      - .address_space:  global
        .offset:         48
        .size:           8
        .value_kind:     global_buffer
    .group_segment_fixed_size: 0
    .kernarg_segment_align: 8
    .kernarg_segment_size: 56
    .language:       OpenCL C
    .language_version:
      - 2
      - 0
    .max_flat_workgroup_size: 64
    .name:           _Z12k_attn_naivePKtS0_S0_S0_PKfPtPf
    .private_segment_fixed_size: 0
    .sgpr_count:     28
    .sgpr_spill_count: 0
    .symbol:         _Z12k_attn_naivePKtS0_S0_S0_PKfPtPf.kd
    .uniform_work_group_size: 1
    .uses_dynamic_stack: false
    .vgpr_count:     184
    .vgpr_spill_count: 0
    .wavefront_size: 64
; __device__ __forceinline__ int lane_id() { int l; asm volatile("v_mbcnt_lo_u32_b32 %0, -1, 0\n\tv_mbcnt_hi_u32_b32 %0, -1, %0" : "=v"(l)); return l; }
; #define LAS __attribute__((address_space(3)))
; __global__ void k_gm(const float* g  , const float* mod, int chunk, float* gmt) {
;     const int idx = blockIdx.x * blockDim.x + threadIdx.x; if (idx >= DEPTH * NB * DM) return;
;     const int c = idx & 1023, b = (idx >> 10) & 15, l = idx >> 14;
;     gmt[idx] = g[l * DM + c] * (1.f + mod[((size_t)l * NB + b) * NMOD + chunk * DM + c]);
; }
; __global__ void __launch_bounds__(NWAVES * 64, 2) mk_fwd(Args args) {
;     extern __shared__ __attribute__((aligned(16))) unsigned char lds[];
;     LAS unsigned char* L = (LAS unsigned char*)lds;
;     volatile LAS unsigned* MISC = (volatile LAS unsigned*)(L + MISC_OFF);
;     const int wid0 = __builtin_amdgcn_readfirstlane((int)threadIdx.x >> 6);
;     const int G = gridDim.x, bx = blockIdx.x;
;     { const int t0 = wid0 * 64 + lane_id(); for (int u = t0; u < (LDS_BYTES - LDSCTL_OFF) / 4; u += NWAVES * 64) ((LAS unsigned*)(L + LDSCTL_OFF))[u] = 0u; }
;     __syncthreads();
;     const int lo = __builtin_amdgcn_readfirstlane(args.ph_lo), hi = __builtin_amdgcn_readfirstlane(args.ph_hi);
  - .agpr_count:     0
    .args:
      - .address_space:  global
        .offset:         0
        .size:           8
        .value_kind:     global_buffer
      - .address_space:  global
        .offset:         8
        .size:           8
        .value_kind:     global_buffer
      - .offset:         16
        .size:           4
        .value_kind:     by_value
      - .address_space:  global
        .offset:         24
        .size:           8
        .value_kind:     global_buffer
      - .offset:         32
        .size:           4
        .value_kind:     hidden_block_count_x
      - .offset:         36
        .size:           4
        .value_kind:     hidden_block_count_y
      - .offset:         40
        .size:           4
        .value_kind:     hidden_block_count_z
      - .offset:         44
        .size:           2
        .value_kind:     hidden_group_size_x
      - .offset:         46
        .size:           2
        .value_kind:     hidden_group_size_y
      - .offset:         48
        .size:           2
        .value_kind:     hidden_group_size_z
      - .offset:         50
        .size:           2
        .value_kind:     hidden_remainder_x
      - .offset:         52
        .size:           2
        .value_kind:     hidden_remainder_y
      - .offset:         54
        .size:           2
        .value_kind:     hidden_remainder_z
      - .offset:         72
        .size:           8
        .value_kind:     hidden_global_offset_x
      - .offset:         80
        .size:           8
        .value_kind:     hidden_global_offset_y
      - .offset:         88
        .size:           8
        .value_kind:     hidden_global_offset_z
      - .offset:         96
        .size:           2
        .value_kind:     hidden_grid_dims
    .group_segment_fixed_size: 0
    .kernarg_segment_align: 8
    .kernarg_segment_size: 288
    .language:       OpenCL C
    .language_version:
      - 2
      - 0
    .max_flat_workgroup_size: 1024
    .name:           _Z4k_gmPKfS0_iPf
    .private_segment_fixed_size: 0
    .sgpr_count:     14
    .sgpr_spill_count: 0
    .symbol:         _Z4k_gmPKfS0_iPf.kd
    .uniform_work_group_size: 1
    .uses_dynamic_stack: false
    .vgpr_count:     8
    .vgpr_spill_count: 0
    .wavefront_size: 64
  - .agpr_count:     0
    .args:
      - .offset:         0
        .size:           192
        .value_kind:     by_value
      - .offset:         192
        .size:           4
        .value_kind:     hidden_block_count_x
      - .offset:         196
        .size:           4
        .value_kind:     hidden_block_count_y
      - .offset:         200
        .size:           4
        .value_kind:     hidden_block_count_z
      - .offset:         204
        .size:           2
        .value_kind:     hidden_group_size_x
      - .offset:         206
        .size:           2
        .value_kind:     hidden_group_size_y
      - .offset:         208
        .size:           2
        .value_kind:     hidden_group_size_z
      - .offset:         210
        .size:           2
        .value_kind:     hidden_remainder_x
      - .offset:         212
        .size:           2
        .value_kind:     hidden_remainder_y
      - .offset:         214
        .size:           2
        .value_kind:     hidden_remainder_z
      - .offset:         232
        .size:           8
        .value_kind:     hidden_global_offset_x
      - .offset:         240
        .size:           8
        .value_kind:     hidden_global_offset_y
      - .offset:         248
        .size:           8
        .value_kind:     hidden_global_offset_z
      - .offset:         256
        .size:           2
        .value_kind:     hidden_grid_dims
      - .offset:         312
        .size:           4
        .value_kind:     hidden_dynamic_lds_size
    .group_segment_fixed_size: 0
    .kernarg_segment_align: 8
    .kernarg_segment_size: 448
    .language:       OpenCL C
    .language_version:
      - 2
      - 0
    .max_flat_workgroup_size: 512
    .name:           _Z6mk_fwd4Args
    .private_segment_fixed_size: 0
    .sgpr_count:     105
    .sgpr_spill_count: 119
    .symbol:         _Z6mk_fwd4Args.kd
    .uniform_work_group_size: 1
    .uses_dynamic_stack: false
    .vgpr_count:     256
    .vgpr_spill_count: 0
    .wavefront_size: 64
